# branch-merge scratch T stored/loaded in a lane-linear dense layout (full 128B lines per store request) in G4 epilogue stores and G5 epilogue loads; on top of v9
# baseline (speedup 1.0000x reference)
.LBB0_2202:
	s_and_b32 vcc_lo, s1, 1
	s_lshl_b32 vcc_lo, vcc_lo, 14
	s_and_b32 vcc_hi, s1, 2
	s_lshl_b32 vcc_hi, vcc_hi, 16
	s_add_i32 vcc_lo, vcc_lo, vcc_hi
	s_lshl_b32 vcc_hi, s0, 19
	s_add_i32 vcc_lo, vcc_lo, vcc_hi
	v_and_b32_e32 v216, 15, v141
	v_lshlrev_b32_e32 v216, 4, v216
	v_lshrrev_b32_e32 v217, 6, v141
	v_lshl_add_u32 v216, v217, 13, v216
	v_and_b32_e32 v217, 0x78, v140
	v_lshl_add_u32 v216, v217, 6, v216
	v_add_u32_e32 v216, vcc_lo, v216
	v_mov_b32_e32 v217, 0
	v_lshl_add_u32 v130, s0, 8, v141
	v_ashrrev_i32_e32 v131, 31, v130
	s_lshl_b32 s0, s1, 8
	v_lshlrev_b64 v[130:131], 10, v[130:131]
	s_ashr_i32 s1, s0, 31
	v_lshl_add_u64 v[130:131], v[130:131], 0, s[0:1]
	v_or_b32_e32 v130, v130, v140
	v_lshlrev_b64 v[146:147], 1, v[130:131]
	v_lshl_add_u64 v[148:149], s[6:7], 0, v[146:147]
	global_load_dwordx4 v[152:155], v[148:149], off
	global_load_dwordx4 v[156:159], v[148:149], off offset:256
	v_add_co_u32_e32 v160, vcc, s75, v148
	v_lshl_add_u64 v[146:147], s[4:5], 0, v[216:217]
	s_nop 0
	v_addc_co_u32_e32 v161, vcc, 0, v149, vcc
	global_load_dwordx4 v[130:133], v[160:161], off offset:256
	s_nop 0
	global_load_dwordx4 v[160:163], v[160:161], off
	s_mov_b32 s0, 0x10000
	s_mov_b32 s1, 0x18000
	s_mov_b64 s[50:51], 0x10000
	s_waitcnt vmcnt(0)
	v_lshlrev_b32_e32 v164, 16, v152
	v_and_b32_e32 v165, 0xffff0000, v152
	v_lshlrev_b32_e32 v152, 16, v153
	v_and_b32_e32 v153, 0xffff0000, v153
	v_lshlrev_b32_e32 v166, 16, v154
	v_and_b32_e32 v167, 0xffff0000, v154
	v_lshlrev_b32_e32 v154, 16, v155
	v_and_b32_e32 v155, 0xffff0000, v155
	v_pk_mul_f32 v[128:129], v[128:129], v[152:153]
	v_pk_mul_f32 v[126:127], v[126:127], v[164:165]
	v_pk_mul_f32 v[152:153], v[124:125], v[154:155]
	v_pk_mul_f32 v[124:125], v[122:123], v[166:167]
	v_cvt_pk_bf16_f32 v122, v126, v127
	v_cvt_pk_bf16_f32 v123, v128, v129
	v_lshlrev_b32_e32 v126, 16, v158
	v_cvt_pk_bf16_f32 v124, v124, v125
	v_cvt_pk_bf16_f32 v125, v152, v153
	global_store_dwordx4 v[146:147], v[122:125], off
	v_and_b32_e32 v127, 0xffff0000, v158
	v_lshlrev_b32_e32 v128, 16, v159
	v_lshlrev_b32_e32 v122, 16, v156
	v_and_b32_e32 v123, 0xffff0000, v156
	v_and_b32_e32 v129, 0xffff0000, v159
	v_lshlrev_b32_e32 v124, 16, v157
	v_and_b32_e32 v125, 0xffff0000, v157
	v_pk_mul_f32 v[118:119], v[118:119], v[122:123]
	v_pk_mul_f32 v[122:123], v[116:117], v[128:129]
	v_pk_mul_f32 v[116:117], v[114:115], v[126:127]
	v_pk_mul_f32 v[120:121], v[120:121], v[124:125]
	v_cvt_pk_bf16_f32 v114, v118, v119
	v_add_co_u32_e32 v118, vcc, s0, v148
	v_cvt_pk_bf16_f32 v115, v120, v121
	v_cvt_pk_bf16_f32 v116, v116, v117
	v_cvt_pk_bf16_f32 v117, v122, v123
	global_store_dwordx4 v[146:147], v[114:117], off offset:256
	v_lshlrev_b32_e32 v122, 16, v160
	v_and_b32_e32 v123, 0xffff0000, v160
	v_addc_co_u32_e32 v119, vcc, 0, v149, vcc
	v_lshlrev_b32_e32 v126, 16, v162
	v_and_b32_e32 v127, 0xffff0000, v162
	v_lshlrev_b32_e32 v128, 16, v163
	v_and_b32_e32 v129, 0xffff0000, v163
	v_pk_mul_f32 v[110:111], v[110:111], v[122:123]
	global_load_dwordx4 v[114:117], v[118:119], off offset:256
	s_nop 0
	global_load_dwordx4 v[118:121], v[118:119], off
	v_lshlrev_b32_e32 v124, 16, v161
	v_and_b32_e32 v125, 0xffff0000, v161
	v_pk_mul_f32 v[122:123], v[108:109], v[128:129]
	v_pk_mul_f32 v[108:109], v[106:107], v[126:127]
	v_cvt_pk_bf16_f32 v106, v110, v111
	v_add_co_u32_e32 v110, vcc, s75, v146
	v_pk_mul_f32 v[112:113], v[112:113], v[124:125]
	s_nop 0
	v_addc_co_u32_e32 v111, vcc, 0, v147, vcc
	v_cvt_pk_bf16_f32 v107, v112, v113
	v_cvt_pk_bf16_f32 v108, v108, v109
	v_cvt_pk_bf16_f32 v109, v122, v123
	global_store_dwordx4 v[110:111], v[106:109], off
	v_lshlrev_b32_e32 v112, 16, v132
	v_and_b32_e32 v113, 0xffff0000, v132
	v_lshlrev_b32_e32 v106, 16, v130
	v_and_b32_e32 v107, 0xffff0000, v130
	v_lshlrev_b32_e32 v122, 16, v133
	v_and_b32_e32 v123, 0xffff0000, v133
	v_lshlrev_b32_e32 v108, 16, v131
	v_and_b32_e32 v109, 0xffff0000, v131
	v_pk_mul_f32 v[102:103], v[102:103], v[106:107]
	v_pk_mul_f32 v[106:107], v[100:101], v[122:123]
	v_pk_mul_f32 v[100:101], v[98:99], v[112:113]
	v_pk_mul_f32 v[104:105], v[104:105], v[108:109]
	v_cvt_pk_bf16_f32 v98, v102, v103
	v_add_co_u32_e32 v102, vcc, s1, v148
	v_cvt_pk_bf16_f32 v99, v104, v105
	v_cvt_pk_bf16_f32 v100, v100, v101
	v_cvt_pk_bf16_f32 v101, v106, v107
	global_store_dwordx4 v[110:111], v[98:101], off offset:256
	s_nop 0
	v_addc_co_u32_e32 v103, vcc, 0, v149, vcc
	global_load_dwordx4 v[98:101], v[102:103], off offset:256
	s_nop 0
	global_load_dwordx4 v[102:105], v[102:103], off
	s_waitcnt vmcnt(4)
	v_lshlrev_b32_e32 v106, 16, v118
	v_and_b32_e32 v107, 0xffff0000, v118
	v_lshlrev_b32_e32 v110, 16, v120
	v_and_b32_e32 v111, 0xffff0000, v120
	v_lshlrev_b32_e32 v112, 16, v121
	v_and_b32_e32 v113, 0xffff0000, v121
	v_pk_mul_f32 v[94:95], v[94:95], v[106:107]
	v_lshlrev_b32_e32 v108, 16, v119
	v_and_b32_e32 v109, 0xffff0000, v119
	v_pk_mul_f32 v[106:107], v[92:93], v[112:113]
	v_pk_mul_f32 v[92:93], v[90:91], v[110:111]
	v_cvt_pk_bf16_f32 v90, v94, v95
	v_add_co_u32_e32 v94, vcc, s0, v146
	v_pk_mul_f32 v[96:97], v[96:97], v[108:109]
	s_nop 0
	v_addc_co_u32_e32 v95, vcc, 0, v147, vcc
	v_cvt_pk_bf16_f32 v91, v96, v97
	v_cvt_pk_bf16_f32 v92, v92, v93
	v_cvt_pk_bf16_f32 v93, v106, v107
	global_store_dwordx4 v[94:95], v[90:93], off
	v_lshlrev_b32_e32 v96, 16, v116
	v_and_b32_e32 v97, 0xffff0000, v116
	v_lshlrev_b32_e32 v90, 16, v114
	v_and_b32_e32 v91, 0xffff0000, v114
	v_lshlrev_b32_e32 v106, 16, v117
	v_and_b32_e32 v107, 0xffff0000, v117
	v_lshlrev_b32_e32 v92, 16, v115
	v_and_b32_e32 v93, 0xffff0000, v115
	v_pk_mul_f32 v[86:87], v[86:87], v[90:91]
	v_pk_mul_f32 v[90:91], v[84:85], v[106:107]
	v_pk_mul_f32 v[84:85], v[82:83], v[96:97]
	s_mov_b32 s0, 0x40000
	v_pk_mul_f32 v[88:89], v[88:89], v[92:93]
	v_cvt_pk_bf16_f32 v82, v86, v87
	v_add_co_u32_e32 v86, vcc, s0, v148
	v_cvt_pk_bf16_f32 v83, v88, v89
	v_cvt_pk_bf16_f32 v84, v84, v85
	v_cvt_pk_bf16_f32 v85, v90, v91
	global_store_dwordx4 v[94:95], v[82:85], off offset:256
	s_waitcnt vmcnt(2)
	v_lshlrev_b32_e32 v90, 16, v102
	v_and_b32_e32 v91, 0xffff0000, v102
	v_addc_co_u32_e32 v87, vcc, 0, v149, vcc
	v_lshlrev_b32_e32 v94, 16, v104
	v_and_b32_e32 v95, 0xffff0000, v104
	v_lshlrev_b32_e32 v96, 16, v105
	v_and_b32_e32 v97, 0xffff0000, v105
	v_pk_mul_f32 v[78:79], v[78:79], v[90:91]
	global_load_dwordx4 v[82:85], v[86:87], off offset:256
	s_nop 0
	global_load_dwordx4 v[86:89], v[86:87], off
	v_lshlrev_b32_e32 v92, 16, v103
	v_and_b32_e32 v93, 0xffff0000, v103
	v_pk_mul_f32 v[90:91], v[76:77], v[96:97]
	v_pk_mul_f32 v[76:77], v[74:75], v[94:95]
	v_cvt_pk_bf16_f32 v74, v78, v79
	v_add_co_u32_e32 v78, vcc, s1, v146
	v_pk_mul_f32 v[80:81], v[80:81], v[92:93]
	s_nop 0
	v_addc_co_u32_e32 v79, vcc, 0, v147, vcc
	v_cvt_pk_bf16_f32 v75, v80, v81
	v_cvt_pk_bf16_f32 v76, v76, v77
	v_cvt_pk_bf16_f32 v77, v90, v91
	global_store_dwordx4 v[78:79], v[74:77], off
	v_lshlrev_b32_e32 v80, 16, v100
	v_and_b32_e32 v81, 0xffff0000, v100
	v_lshlrev_b32_e32 v74, 16, v98
	v_and_b32_e32 v75, 0xffff0000, v98
	v_lshlrev_b32_e32 v90, 16, v101
	v_and_b32_e32 v91, 0xffff0000, v101
	v_lshlrev_b32_e32 v76, 16, v99
	v_and_b32_e32 v77, 0xffff0000, v99
	v_pk_mul_f32 v[70:71], v[70:71], v[74:75]
	v_pk_mul_f32 v[74:75], v[68:69], v[90:91]
	v_pk_mul_f32 v[68:69], v[66:67], v[80:81]
	s_mov_b32 s1, 0x48000
	v_pk_mul_f32 v[72:73], v[72:73], v[76:77]
	v_cvt_pk_bf16_f32 v66, v70, v71
	v_add_co_u32_e32 v70, vcc, s1, v148
	v_cvt_pk_bf16_f32 v67, v72, v73
	v_cvt_pk_bf16_f32 v68, v68, v69
	v_cvt_pk_bf16_f32 v69, v74, v75
	global_store_dwordx4 v[78:79], v[66:69], off offset:256
	s_nop 0
	v_addc_co_u32_e32 v71, vcc, 0, v149, vcc
	global_load_dwordx4 v[66:69], v[70:71], off offset:256
	s_nop 0
	global_load_dwordx4 v[70:73], v[70:71], off
	s_waitcnt vmcnt(4)
	v_lshlrev_b32_e32 v74, 16, v86
	v_and_b32_e32 v75, 0xffff0000, v86
	v_lshlrev_b32_e32 v78, 16, v88
	v_and_b32_e32 v79, 0xffff0000, v88
	v_lshlrev_b32_e32 v80, 16, v89
	v_and_b32_e32 v81, 0xffff0000, v89
	v_pk_mul_f32 v[62:63], v[62:63], v[74:75]
	v_lshlrev_b32_e32 v76, 16, v87
	v_and_b32_e32 v77, 0xffff0000, v87
	v_pk_mul_f32 v[74:75], v[60:61], v[80:81]
	v_pk_mul_f32 v[60:61], v[58:59], v[78:79]
	v_cvt_pk_bf16_f32 v58, v62, v63
	v_add_co_u32_e32 v62, vcc, s0, v146
	v_pk_mul_f32 v[64:65], v[64:65], v[76:77]
	s_nop 0
	v_addc_co_u32_e32 v63, vcc, 0, v147, vcc
	v_cvt_pk_bf16_f32 v59, v64, v65
	v_cvt_pk_bf16_f32 v60, v60, v61
	v_cvt_pk_bf16_f32 v61, v74, v75
	global_store_dwordx4 v[62:63], v[58:61], off
	v_lshlrev_b32_e32 v64, 16, v84
	v_and_b32_e32 v65, 0xffff0000, v84
	v_lshlrev_b32_e32 v58, 16, v82
	v_and_b32_e32 v59, 0xffff0000, v82
	v_lshlrev_b32_e32 v74, 16, v85
	v_and_b32_e32 v75, 0xffff0000, v85
	v_lshlrev_b32_e32 v60, 16, v83
	v_and_b32_e32 v61, 0xffff0000, v83
	v_pk_mul_f32 v[54:55], v[54:55], v[58:59]
	v_pk_mul_f32 v[58:59], v[52:53], v[74:75]
	v_pk_mul_f32 v[52:53], v[50:51], v[64:65]
	s_mov_b32 s0, 0x50000
	v_pk_mul_f32 v[56:57], v[56:57], v[60:61]
	v_cvt_pk_bf16_f32 v50, v54, v55
	v_add_co_u32_e32 v54, vcc, s0, v148
	v_cvt_pk_bf16_f32 v51, v56, v57
	v_cvt_pk_bf16_f32 v52, v52, v53
	v_cvt_pk_bf16_f32 v53, v58, v59
	global_store_dwordx4 v[62:63], v[50:53], off offset:256
	s_waitcnt vmcnt(2)
	v_lshlrev_b32_e32 v58, 16, v70
	v_and_b32_e32 v59, 0xffff0000, v70
	v_addc_co_u32_e32 v55, vcc, 0, v149, vcc
	v_lshlrev_b32_e32 v62, 16, v72
	v_and_b32_e32 v63, 0xffff0000, v72
	v_lshlrev_b32_e32 v64, 16, v73
	v_and_b32_e32 v65, 0xffff0000, v73
	v_pk_mul_f32 v[46:47], v[46:47], v[58:59]
	global_load_dwordx4 v[50:53], v[54:55], off offset:256
	s_nop 0
	global_load_dwordx4 v[54:57], v[54:55], off
	v_lshlrev_b32_e32 v60, 16, v71
	v_and_b32_e32 v61, 0xffff0000, v71
	v_pk_mul_f32 v[58:59], v[44:45], v[64:65]
	v_pk_mul_f32 v[44:45], v[42:43], v[62:63]
	v_cvt_pk_bf16_f32 v42, v46, v47
	v_add_co_u32_e32 v46, vcc, s1, v146
	v_pk_mul_f32 v[48:49], v[48:49], v[60:61]
	s_nop 0
	v_addc_co_u32_e32 v47, vcc, 0, v147, vcc
	v_cvt_pk_bf16_f32 v43, v48, v49
	v_cvt_pk_bf16_f32 v44, v44, v45
	v_cvt_pk_bf16_f32 v45, v58, v59
	global_store_dwordx4 v[46:47], v[42:45], off
	v_lshlrev_b32_e32 v48, 16, v68
	v_and_b32_e32 v49, 0xffff0000, v68
	v_lshlrev_b32_e32 v42, 16, v66
	v_and_b32_e32 v43, 0xffff0000, v66
	v_lshlrev_b32_e32 v58, 16, v69
	v_and_b32_e32 v59, 0xffff0000, v69
	v_lshlrev_b32_e32 v44, 16, v67
	v_and_b32_e32 v45, 0xffff0000, v67
	v_pk_mul_f32 v[38:39], v[38:39], v[42:43]
	v_pk_mul_f32 v[42:43], v[36:37], v[58:59]
	v_pk_mul_f32 v[36:37], v[34:35], v[48:49]
	s_mov_b32 s1, 0x58000
	v_pk_mul_f32 v[40:41], v[40:41], v[44:45]
	v_cvt_pk_bf16_f32 v34, v38, v39
	v_add_co_u32_e32 v38, vcc, s1, v148
	v_cvt_pk_bf16_f32 v35, v40, v41
	v_cvt_pk_bf16_f32 v36, v36, v37
	v_cvt_pk_bf16_f32 v37, v42, v43
	global_store_dwordx4 v[46:47], v[34:37], off offset:256
	s_nop 0
	v_addc_co_u32_e32 v39, vcc, 0, v149, vcc
	global_load_dwordx4 v[34:37], v[38:39], off offset:256
	s_nop 0
	global_load_dwordx4 v[38:41], v[38:39], off
	s_waitcnt vmcnt(4)
	v_lshlrev_b32_e32 v42, 16, v54
	v_and_b32_e32 v43, 0xffff0000, v54
	v_lshlrev_b32_e32 v46, 16, v56
	v_and_b32_e32 v47, 0xffff0000, v56
	v_lshlrev_b32_e32 v48, 16, v57
	v_and_b32_e32 v49, 0xffff0000, v57
	v_pk_mul_f32 v[30:31], v[30:31], v[42:43]
	v_lshlrev_b32_e32 v44, 16, v55
	v_and_b32_e32 v45, 0xffff0000, v55
	v_pk_mul_f32 v[42:43], v[28:29], v[48:49]
	v_pk_mul_f32 v[28:29], v[26:27], v[46:47]
	v_cvt_pk_bf16_f32 v26, v30, v31
	v_add_co_u32_e32 v30, vcc, s0, v146
	v_pk_mul_f32 v[32:33], v[32:33], v[44:45]
	s_nop 0
	v_addc_co_u32_e32 v31, vcc, 0, v147, vcc
	v_cvt_pk_bf16_f32 v27, v32, v33
	v_cvt_pk_bf16_f32 v28, v28, v29
	v_cvt_pk_bf16_f32 v29, v42, v43
	global_store_dwordx4 v[30:31], v[26:29], off
	v_lshlrev_b32_e32 v32, 16, v52
	v_and_b32_e32 v33, 0xffff0000, v52
	v_lshlrev_b32_e32 v26, 16, v50
	v_and_b32_e32 v27, 0xffff0000, v50
	v_lshlrev_b32_e32 v28, 16, v51
	v_and_b32_e32 v29, 0xffff0000, v51
	v_lshlrev_b32_e32 v42, 16, v53
	v_and_b32_e32 v43, 0xffff0000, v53
	v_pk_mul_f32 v[16:17], v[16:17], v[28:29]
	v_pk_mul_f32 v[14:15], v[14:15], v[26:27]
	v_pk_mul_f32 v[26:27], v[12:13], v[42:43]
	v_pk_mul_f32 v[12:13], v[10:11], v[32:33]
	v_cvt_pk_bf16_f32 v10, v14, v15
	v_cvt_pk_bf16_f32 v11, v16, v17
	s_waitcnt vmcnt(1)
	v_lshlrev_b32_e32 v14, 16, v40
	v_cvt_pk_bf16_f32 v12, v12, v13
	v_cvt_pk_bf16_f32 v13, v26, v27
	global_store_dwordx4 v[30:31], v[10:13], off offset:256
	v_and_b32_e32 v15, 0xffff0000, v40
	v_lshlrev_b32_e32 v16, 16, v41
	v_lshlrev_b32_e32 v10, 16, v38
	v_and_b32_e32 v11, 0xffff0000, v38
	v_lshlrev_b32_e32 v12, 16, v39
	v_and_b32_e32 v13, 0xffff0000, v39
	v_pk_mul_f32 v[10:11], v[22:23], v[10:11]
	v_and_b32_e32 v17, 0xffff0000, v41
	v_pk_mul_f32 v[24:25], v[24:25], v[12:13]
	v_cvt_pk_bf16_f32 v12, v10, v11
	v_add_co_u32_e32 v10, vcc, s1, v146
	v_pk_mul_f32 v[16:17], v[20:21], v[16:17]
	v_pk_mul_f32 v[14:15], v[18:19], v[14:15]
	v_cvt_pk_bf16_f32 v13, v24, v25
	v_addc_co_u32_e32 v11, vcc, 0, v147, vcc
	v_cvt_pk_bf16_f32 v14, v14, v15
	v_cvt_pk_bf16_f32 v15, v16, v17
	global_store_dwordx4 v[10:11], v[12:15], off
	v_lshlrev_b32_e32 v16, 16, v36
	v_and_b32_e32 v17, 0xffff0000, v36
	v_lshlrev_b32_e32 v12, 16, v34
	v_and_b32_e32 v13, 0xffff0000, v34
	v_lshlrev_b32_e32 v18, 16, v37
	v_and_b32_e32 v19, 0xffff0000, v37
	v_lshlrev_b32_e32 v14, 16, v35
	v_and_b32_e32 v15, 0xffff0000, v35
	v_pk_mul_f32 v[6:7], v[6:7], v[12:13]
	v_pk_mul_f32 v[12:13], v[4:5], v[18:19]
	v_pk_mul_f32 v[4:5], v[2:3], v[16:17]
	v_pk_mul_f32 v[8:9], v[8:9], v[14:15]
	v_cvt_pk_bf16_f32 v2, v6, v7
	s_mov_b64 s[0:1], -1
	v_cvt_pk_bf16_f32 v3, v8, v9
	v_cvt_pk_bf16_f32 v4, v4, v5
	v_cvt_pk_bf16_f32 v5, v12, v13
	global_store_dwordx4 v[10:11], v[2:5], off offset:256
	s_andn2_b64 vcc, exec, s[16:17]
	s_cbranch_vccnz .LBB0_2191
	s_andn2_b64 vcc, exec, s[2:3]
	s_cbranch_vccnz .LBB0_2190
	s_barrier
	s_branch .LBB0_2190

.LBB0_2280:
	s_and_b32 vcc_lo, s23, 1
	s_lshl_b32 vcc_lo, vcc_lo, 14
	s_and_b32 vcc_hi, s23, 2
	s_lshl_b32 vcc_hi, vcc_hi, 16
	s_add_i32 vcc_lo, vcc_lo, vcc_hi
	s_lshl_b32 vcc_hi, s22, 19
	s_add_i32 vcc_lo, vcc_lo, vcc_hi
	v_and_b32_e32 v216, 15, v153
	v_lshlrev_b32_e32 v216, 4, v216
	v_lshrrev_b32_e32 v217, 6, v153
	v_lshl_add_u32 v216, v217, 13, v216
	v_and_b32_e32 v217, 0x78, v152
	v_lshl_add_u32 v216, v217, 6, v216
	v_add_u32_e32 v216, vcc_lo, v216
	v_mov_b32_e32 v217, 0
	v_lshl_add_u32 v130, s22, 8, v153
	v_ashrrev_i32_e32 v131, 31, v130
	s_lshl_b32 s22, s23, 8
	v_lshlrev_b64 v[130:131], 10, v[130:131]
	s_ashr_i32 s23, s22, 31
	v_lshl_add_u64 v[130:131], v[130:131], 0, s[22:23]
	v_or_b32_e32 v130, v130, v152
	v_lshlrev_b64 v[158:159], 1, v[130:131]
	v_lshl_add_u64 v[160:161], s[4:5], 0, v[158:159]
	v_lshl_add_u64 v[162:163], s[2:3], 0, v[216:217]
	global_load_dwordx4 v[166:169], v[160:161], off
	global_load_dwordx4 v[170:173], v[162:163], off
	global_load_dwordx4 v[174:177], v[160:161], off offset:256
	global_load_dwordx4 v[178:181], v[162:163], off offset:256
	v_add_co_u32_e32 v138, vcc, s75, v162
	s_mov_b64 s[22:23], 0x8000
	s_nop 0
	v_addc_co_u32_e32 v139, vcc, 0, v163, vcc
	v_add_co_u32_e32 v142, vcc, s75, v160
	global_load_dwordx4 v[138:141], v[138:139], off
	s_nop 0
	v_addc_co_u32_e32 v143, vcc, 0, v161, vcc
	global_load_dwordx4 v[142:145], v[142:143], off
	v_lshl_add_u64 v[130:131], v[162:163], 0, s[22:23]
	v_lshl_add_u64 v[134:135], v[160:161], 0, s[22:23]
	global_load_dwordx4 v[130:133], v[130:131], off offset:256
	v_lshl_add_u64 v[158:159], s[6:7], 0, v[158:159]
	global_load_dwordx4 v[134:137], v[134:135], off offset:256
	s_mov_b32 s11, 0x10000
	s_mov_b64 s[50:51], 0x10000
	s_mov_b32 s15, 0x18000
	s_mov_b64 s[12:13], 0x18000
	s_mov_b64 s[22:23], -1
	s_waitcnt vmcnt(0)
	v_lshlrev_b32_e32 v182, 16, v166
	v_and_b32_e32 v183, 0xffff0000, v166
	v_lshlrev_b32_e32 v166, 16, v167
	v_and_b32_e32 v167, 0xffff0000, v167
	v_lshlrev_b32_e32 v184, 16, v168
	v_and_b32_e32 v185, 0xffff0000, v168
	v_lshlrev_b32_e32 v168, 16, v169
	v_and_b32_e32 v169, 0xffff0000, v169
	v_lshlrev_b32_e32 v186, 16, v170
	v_and_b32_e32 v187, 0xffff0000, v170
	v_lshlrev_b32_e32 v170, 16, v171
	v_and_b32_e32 v171, 0xffff0000, v171
	v_lshlrev_b32_e32 v188, 16, v172
	v_and_b32_e32 v189, 0xffff0000, v172
	v_lshlrev_b32_e32 v172, 16, v173
	v_and_b32_e32 v173, 0xffff0000, v173
	v_pk_fma_f32 v[128:129], v[128:129], v[166:167], v[170:171]
	v_pk_fma_f32 v[126:127], v[126:127], v[182:183], v[186:187]
	v_pk_fma_f32 v[166:167], v[124:125], v[168:169], v[172:173]
	v_pk_fma_f32 v[124:125], v[122:123], v[184:185], v[188:189]
	v_cvt_pk_bf16_f32 v122, v126, v127
	v_cvt_pk_bf16_f32 v123, v128, v129
	v_lshlrev_b32_e32 v126, 16, v176
	v_cvt_pk_bf16_f32 v124, v124, v125
	v_cvt_pk_bf16_f32 v125, v166, v167
	global_store_dwordx4 v[158:159], v[122:125], off
	v_and_b32_e32 v127, 0xffff0000, v176
	v_lshlrev_b32_e32 v128, 16, v177
	v_lshlrev_b32_e32 v122, 16, v174
	v_and_b32_e32 v123, 0xffff0000, v174
	v_and_b32_e32 v129, 0xffff0000, v177
	v_lshlrev_b32_e32 v166, 16, v178
	v_and_b32_e32 v167, 0xffff0000, v178
	v_lshlrev_b32_e32 v170, 16, v180
	v_and_b32_e32 v171, 0xffff0000, v180
	v_lshlrev_b32_e32 v172, 16, v181
	v_and_b32_e32 v173, 0xffff0000, v181
	v_lshlrev_b32_e32 v124, 16, v175
	v_and_b32_e32 v125, 0xffff0000, v175
	v_lshlrev_b32_e32 v168, 16, v179
	v_and_b32_e32 v169, 0xffff0000, v179
	v_pk_fma_f32 v[118:119], v[118:119], v[122:123], v[166:167]
	v_pk_fma_f32 v[122:123], v[116:117], v[128:129], v[172:173]
	v_pk_fma_f32 v[116:117], v[114:115], v[126:127], v[170:171]
	v_pk_fma_f32 v[120:121], v[120:121], v[124:125], v[168:169]
	v_cvt_pk_bf16_f32 v114, v118, v119
	v_lshlrev_b32_e32 v166, 16, v142
	v_cvt_pk_bf16_f32 v115, v120, v121
	v_cvt_pk_bf16_f32 v116, v116, v117
	v_cvt_pk_bf16_f32 v117, v122, v123
	v_add_co_u32_e32 v122, vcc, s11, v162
	global_store_dwordx4 v[158:159], v[114:117], off offset:256
	s_nop 0
	v_addc_co_u32_e32 v123, vcc, 0, v163, vcc
	v_add_co_u32_e32 v126, vcc, s11, v160
	v_and_b32_e32 v167, 0xffff0000, v142
	v_lshlrev_b32_e32 v170, 16, v138
	v_and_b32_e32 v171, 0xffff0000, v138
	v_lshl_add_u64 v[114:115], v[162:163], 0, s[50:51]
	v_lshl_add_u64 v[118:119], v[160:161], 0, s[50:51]
	v_addc_co_u32_e32 v127, vcc, 0, v161, vcc
	v_lshlrev_b32_e32 v142, 16, v143
	v_and_b32_e32 v143, 0xffff0000, v143
	v_lshlrev_b32_e32 v168, 16, v144
	v_and_b32_e32 v169, 0xffff0000, v144
	v_lshlrev_b32_e32 v144, 16, v145
	v_and_b32_e32 v145, 0xffff0000, v145
	v_lshlrev_b32_e32 v138, 16, v139
	v_and_b32_e32 v139, 0xffff0000, v139
	v_lshlrev_b32_e32 v172, 16, v140
	v_and_b32_e32 v173, 0xffff0000, v140
	v_lshlrev_b32_e32 v140, 16, v141
	v_and_b32_e32 v141, 0xffff0000, v141
	v_pk_fma_f32 v[110:111], v[110:111], v[166:167], v[170:171]
	global_load_dwordx4 v[114:117], v[114:115], off offset:256
	v_pk_fma_f32 v[112:113], v[112:113], v[142:143], v[138:139]
	global_load_dwordx4 v[118:121], v[118:119], off offset:256
	v_pk_fma_f32 v[138:139], v[108:109], v[144:145], v[140:141]
	global_load_dwordx4 v[122:125], v[122:123], off
	v_pk_fma_f32 v[108:109], v[106:107], v[168:169], v[172:173]
	global_load_dwordx4 v[126:129], v[126:127], off
	v_cvt_pk_bf16_f32 v106, v110, v111
	v_add_co_u32_e32 v110, vcc, s75, v158
	v_cvt_pk_bf16_f32 v107, v112, v113
	v_cvt_pk_bf16_f32 v108, v108, v109
	v_cvt_pk_bf16_f32 v109, v138, v139
	v_lshlrev_b32_e32 v112, 16, v136
	s_nop 0
	v_addc_co_u32_e32 v111, vcc, 0, v159, vcc
	global_store_dwordx4 v[110:111], v[106:109], off
	v_and_b32_e32 v113, 0xffff0000, v136
	v_lshlrev_b32_e32 v136, 16, v130
	v_lshlrev_b32_e32 v106, 16, v134
	v_and_b32_e32 v107, 0xffff0000, v134
	v_lshlrev_b32_e32 v108, 16, v135
	v_and_b32_e32 v109, 0xffff0000, v135
	v_lshlrev_b32_e32 v134, 16, v137
	v_and_b32_e32 v135, 0xffff0000, v137
	v_and_b32_e32 v137, 0xffff0000, v130
	v_lshlrev_b32_e32 v138, 16, v132
	v_and_b32_e32 v139, 0xffff0000, v132
	v_lshlrev_b32_e32 v132, 16, v133
	v_and_b32_e32 v133, 0xffff0000, v133
	v_lshlrev_b32_e32 v130, 16, v131
	v_and_b32_e32 v131, 0xffff0000, v131
	v_pk_fma_f32 v[102:103], v[102:103], v[106:107], v[136:137]
	v_pk_fma_f32 v[106:107], v[100:101], v[134:135], v[132:133]
	v_pk_fma_f32 v[100:101], v[98:99], v[112:113], v[138:139]
	v_pk_fma_f32 v[104:105], v[104:105], v[108:109], v[130:131]
	v_cvt_pk_bf16_f32 v98, v102, v103
	v_lshl_add_u64 v[102:103], v[160:161], 0, s[12:13]
	v_cvt_pk_bf16_f32 v99, v104, v105
	v_cvt_pk_bf16_f32 v100, v100, v101
	v_cvt_pk_bf16_f32 v101, v106, v107
	v_add_co_u32_e32 v106, vcc, s15, v162
	global_store_dwordx4 v[110:111], v[98:101], off offset:256
	s_nop 0
	v_addc_co_u32_e32 v107, vcc, 0, v163, vcc
	v_add_co_u32_e32 v110, vcc, s15, v160
	global_load_dwordx4 v[106:109], v[106:107], off
	s_nop 0
	v_addc_co_u32_e32 v111, vcc, 0, v161, vcc
	global_load_dwordx4 v[110:113], v[110:111], off
	v_lshl_add_u64 v[98:99], v[162:163], 0, s[12:13]
	global_load_dwordx4 v[98:101], v[98:99], off offset:256
	s_mov_b64 s[12:13], 0x40000
	global_load_dwordx4 v[102:105], v[102:103], off offset:256
	s_waitcnt vmcnt(7)
	v_lshlrev_b32_e32 v134, 16, v122
	v_and_b32_e32 v135, 0xffff0000, v122
	s_waitcnt vmcnt(6)
	v_lshlrev_b32_e32 v130, 16, v126
	v_and_b32_e32 v131, 0xffff0000, v126
	v_lshlrev_b32_e32 v126, 16, v127
	v_and_b32_e32 v127, 0xffff0000, v127
	v_lshlrev_b32_e32 v132, 16, v128
	v_and_b32_e32 v133, 0xffff0000, v128
	v_lshlrev_b32_e32 v128, 16, v129
	v_and_b32_e32 v129, 0xffff0000, v129
	v_lshlrev_b32_e32 v122, 16, v123
	v_and_b32_e32 v123, 0xffff0000, v123
	v_lshlrev_b32_e32 v136, 16, v124
	v_and_b32_e32 v137, 0xffff0000, v124
	v_lshlrev_b32_e32 v124, 16, v125
	v_and_b32_e32 v125, 0xffff0000, v125
	v_pk_fma_f32 v[94:95], v[94:95], v[130:131], v[134:135]
	v_pk_fma_f32 v[96:97], v[96:97], v[126:127], v[122:123]
	v_pk_fma_f32 v[122:123], v[92:93], v[128:129], v[124:125]
	v_pk_fma_f32 v[92:93], v[90:91], v[132:133], v[136:137]
	v_cvt_pk_bf16_f32 v90, v94, v95
	v_add_co_u32_e32 v94, vcc, s11, v158
	v_cvt_pk_bf16_f32 v91, v96, v97
	v_cvt_pk_bf16_f32 v92, v92, v93
	v_cvt_pk_bf16_f32 v93, v122, v123
	v_lshlrev_b32_e32 v96, 16, v120
	s_nop 0
	v_addc_co_u32_e32 v95, vcc, 0, v159, vcc
	global_store_dwordx4 v[94:95], v[90:93], off
	v_and_b32_e32 v97, 0xffff0000, v120
	v_lshlrev_b32_e32 v120, 16, v114
	v_lshlrev_b32_e32 v90, 16, v118
	v_and_b32_e32 v91, 0xffff0000, v118
	v_lshlrev_b32_e32 v92, 16, v119
	v_and_b32_e32 v93, 0xffff0000, v119
	v_lshlrev_b32_e32 v118, 16, v121
	v_and_b32_e32 v119, 0xffff0000, v121
	v_and_b32_e32 v121, 0xffff0000, v114
	v_lshlrev_b32_e32 v122, 16, v116
	v_and_b32_e32 v123, 0xffff0000, v116
	v_lshlrev_b32_e32 v116, 16, v117
	v_and_b32_e32 v117, 0xffff0000, v117
	v_lshlrev_b32_e32 v114, 16, v115
	v_and_b32_e32 v115, 0xffff0000, v115
	v_pk_fma_f32 v[86:87], v[86:87], v[90:91], v[120:121]
	v_pk_fma_f32 v[90:91], v[84:85], v[118:119], v[116:117]
	v_pk_fma_f32 v[84:85], v[82:83], v[96:97], v[122:123]
	s_mov_b32 s11, 0x40000
	v_pk_fma_f32 v[88:89], v[88:89], v[92:93], v[114:115]
	v_cvt_pk_bf16_f32 v82, v86, v87
	s_waitcnt vmcnt(3)
	v_lshlrev_b32_e32 v114, 16, v110
	v_cvt_pk_bf16_f32 v83, v88, v89
	v_cvt_pk_bf16_f32 v84, v84, v85
	v_cvt_pk_bf16_f32 v85, v90, v91
	v_add_co_u32_e32 v90, vcc, s11, v162
	global_store_dwordx4 v[94:95], v[82:85], off offset:256
	s_nop 0
	v_addc_co_u32_e32 v91, vcc, 0, v163, vcc
	v_add_co_u32_e32 v94, vcc, s11, v160
	v_and_b32_e32 v115, 0xffff0000, v110
	v_lshlrev_b32_e32 v118, 16, v106
	v_and_b32_e32 v119, 0xffff0000, v106
	v_lshl_add_u64 v[82:83], v[162:163], 0, s[12:13]
	v_lshl_add_u64 v[86:87], v[160:161], 0, s[12:13]
	v_addc_co_u32_e32 v95, vcc, 0, v161, vcc
	v_lshlrev_b32_e32 v110, 16, v111
	v_and_b32_e32 v111, 0xffff0000, v111
	v_lshlrev_b32_e32 v116, 16, v112
	v_and_b32_e32 v117, 0xffff0000, v112
	v_lshlrev_b32_e32 v112, 16, v113
	v_and_b32_e32 v113, 0xffff0000, v113
	v_lshlrev_b32_e32 v106, 16, v107
	v_and_b32_e32 v107, 0xffff0000, v107
	v_lshlrev_b32_e32 v120, 16, v108
	v_and_b32_e32 v121, 0xffff0000, v108
	v_lshlrev_b32_e32 v108, 16, v109
	v_and_b32_e32 v109, 0xffff0000, v109
	v_pk_fma_f32 v[78:79], v[78:79], v[114:115], v[118:119]
	global_load_dwordx4 v[82:85], v[82:83], off offset:256
	v_pk_fma_f32 v[80:81], v[80:81], v[110:111], v[106:107]
	global_load_dwordx4 v[86:89], v[86:87], off offset:256
	v_pk_fma_f32 v[106:107], v[76:77], v[112:113], v[108:109]
	global_load_dwordx4 v[90:93], v[90:91], off
	v_pk_fma_f32 v[76:77], v[74:75], v[116:117], v[120:121]
	global_load_dwordx4 v[94:97], v[94:95], off
	v_cvt_pk_bf16_f32 v74, v78, v79
	v_add_co_u32_e32 v78, vcc, s15, v158
	v_cvt_pk_bf16_f32 v75, v80, v81
	v_cvt_pk_bf16_f32 v76, v76, v77
	v_cvt_pk_bf16_f32 v77, v106, v107
	s_waitcnt vmcnt(6)
	v_lshlrev_b32_e32 v80, 16, v104
	v_addc_co_u32_e32 v79, vcc, 0, v159, vcc
	global_store_dwordx4 v[78:79], v[74:77], off
	v_and_b32_e32 v81, 0xffff0000, v104
	v_lshlrev_b32_e32 v104, 16, v98
	v_lshlrev_b32_e32 v74, 16, v102
	v_and_b32_e32 v75, 0xffff0000, v102
	v_lshlrev_b32_e32 v76, 16, v103
	v_and_b32_e32 v77, 0xffff0000, v103
	v_lshlrev_b32_e32 v102, 16, v105
	v_and_b32_e32 v103, 0xffff0000, v105
	v_and_b32_e32 v105, 0xffff0000, v98
	v_lshlrev_b32_e32 v106, 16, v100
	v_and_b32_e32 v107, 0xffff0000, v100
	v_lshlrev_b32_e32 v100, 16, v101
	v_and_b32_e32 v101, 0xffff0000, v101
	v_lshlrev_b32_e32 v98, 16, v99
	v_and_b32_e32 v99, 0xffff0000, v99
	v_pk_fma_f32 v[70:71], v[70:71], v[74:75], v[104:105]
	v_pk_fma_f32 v[74:75], v[68:69], v[102:103], v[100:101]
	v_pk_fma_f32 v[68:69], v[66:67], v[80:81], v[106:107]
	s_mov_b32 s15, 0x48000
	v_pk_fma_f32 v[72:73], v[72:73], v[76:77], v[98:99]
	v_cvt_pk_bf16_f32 v66, v70, v71
	s_mov_b64 s[12:13], 0x48000
	v_cvt_pk_bf16_f32 v67, v72, v73
	v_cvt_pk_bf16_f32 v68, v68, v69
	v_cvt_pk_bf16_f32 v69, v74, v75
	v_add_co_u32_e32 v74, vcc, s15, v162
	global_store_dwordx4 v[78:79], v[66:69], off offset:256
	s_nop 0
	v_addc_co_u32_e32 v75, vcc, 0, v163, vcc
	v_add_co_u32_e32 v78, vcc, s15, v160
	global_load_dwordx4 v[74:77], v[74:75], off
	s_nop 0
	v_addc_co_u32_e32 v79, vcc, 0, v161, vcc
	global_load_dwordx4 v[78:81], v[78:79], off
	v_lshl_add_u64 v[66:67], v[162:163], 0, s[12:13]
	v_lshl_add_u64 v[70:71], v[160:161], 0, s[12:13]
	global_load_dwordx4 v[66:69], v[66:67], off offset:256
	s_mov_b64 s[12:13], 0x50000
	global_load_dwordx4 v[70:73], v[70:71], off offset:256
	s_waitcnt vmcnt(7)
	v_lshlrev_b32_e32 v102, 16, v90
	v_and_b32_e32 v103, 0xffff0000, v90
	s_waitcnt vmcnt(6)
	v_lshlrev_b32_e32 v98, 16, v94
	v_and_b32_e32 v99, 0xffff0000, v94
	v_lshlrev_b32_e32 v94, 16, v95
	v_and_b32_e32 v95, 0xffff0000, v95
	v_lshlrev_b32_e32 v100, 16, v96
	v_and_b32_e32 v101, 0xffff0000, v96
	v_lshlrev_b32_e32 v96, 16, v97
	v_and_b32_e32 v97, 0xffff0000, v97
	v_lshlrev_b32_e32 v90, 16, v91
	v_and_b32_e32 v91, 0xffff0000, v91
	v_lshlrev_b32_e32 v104, 16, v92
	v_and_b32_e32 v105, 0xffff0000, v92
	v_lshlrev_b32_e32 v92, 16, v93
	v_and_b32_e32 v93, 0xffff0000, v93
	v_pk_fma_f32 v[62:63], v[62:63], v[98:99], v[102:103]
	v_pk_fma_f32 v[64:65], v[64:65], v[94:95], v[90:91]
	v_pk_fma_f32 v[90:91], v[60:61], v[96:97], v[92:93]
	v_pk_fma_f32 v[60:61], v[58:59], v[100:101], v[104:105]
	v_cvt_pk_bf16_f32 v58, v62, v63
	v_add_co_u32_e32 v62, vcc, s11, v158
	v_cvt_pk_bf16_f32 v59, v64, v65
	v_cvt_pk_bf16_f32 v60, v60, v61
	v_cvt_pk_bf16_f32 v61, v90, v91
	v_lshlrev_b32_e32 v64, 16, v88
	s_nop 0
	v_addc_co_u32_e32 v63, vcc, 0, v159, vcc
	global_store_dwordx4 v[62:63], v[58:61], off
	v_and_b32_e32 v65, 0xffff0000, v88
	v_lshlrev_b32_e32 v88, 16, v82
	v_lshlrev_b32_e32 v58, 16, v86
	v_and_b32_e32 v59, 0xffff0000, v86
	v_lshlrev_b32_e32 v60, 16, v87
	v_and_b32_e32 v61, 0xffff0000, v87
	v_lshlrev_b32_e32 v86, 16, v89
	v_and_b32_e32 v87, 0xffff0000, v89
	v_and_b32_e32 v89, 0xffff0000, v82
	v_lshlrev_b32_e32 v90, 16, v84
	v_and_b32_e32 v91, 0xffff0000, v84
	v_lshlrev_b32_e32 v84, 16, v85
	v_and_b32_e32 v85, 0xffff0000, v85
	v_lshlrev_b32_e32 v82, 16, v83
	v_and_b32_e32 v83, 0xffff0000, v83
	v_pk_fma_f32 v[54:55], v[54:55], v[58:59], v[88:89]
	v_pk_fma_f32 v[58:59], v[52:53], v[86:87], v[84:85]
	v_pk_fma_f32 v[52:53], v[50:51], v[64:65], v[90:91]
	s_mov_b32 s11, 0x50000
	v_pk_fma_f32 v[56:57], v[56:57], v[60:61], v[82:83]
	v_cvt_pk_bf16_f32 v50, v54, v55
	s_waitcnt vmcnt(3)
	v_lshlrev_b32_e32 v82, 16, v78
	v_cvt_pk_bf16_f32 v51, v56, v57
	v_cvt_pk_bf16_f32 v52, v52, v53
	v_cvt_pk_bf16_f32 v53, v58, v59
	v_add_co_u32_e32 v58, vcc, s11, v162
	global_store_dwordx4 v[62:63], v[50:53], off offset:256
	s_nop 0
	v_addc_co_u32_e32 v59, vcc, 0, v163, vcc
	v_add_co_u32_e32 v62, vcc, s11, v160
	v_and_b32_e32 v83, 0xffff0000, v78
	v_lshlrev_b32_e32 v86, 16, v74
	v_and_b32_e32 v87, 0xffff0000, v74
	v_lshl_add_u64 v[50:51], v[162:163], 0, s[12:13]
	v_lshl_add_u64 v[54:55], v[160:161], 0, s[12:13]
	v_addc_co_u32_e32 v63, vcc, 0, v161, vcc
	v_lshlrev_b32_e32 v78, 16, v79
	v_and_b32_e32 v79, 0xffff0000, v79
	v_lshlrev_b32_e32 v84, 16, v80
	v_and_b32_e32 v85, 0xffff0000, v80
	v_lshlrev_b32_e32 v80, 16, v81
	v_and_b32_e32 v81, 0xffff0000, v81
	v_lshlrev_b32_e32 v74, 16, v75
	v_and_b32_e32 v75, 0xffff0000, v75
	v_lshlrev_b32_e32 v88, 16, v76
	v_and_b32_e32 v89, 0xffff0000, v76
	v_lshlrev_b32_e32 v76, 16, v77
	v_and_b32_e32 v77, 0xffff0000, v77
	v_pk_fma_f32 v[46:47], v[46:47], v[82:83], v[86:87]
	global_load_dwordx4 v[50:53], v[50:51], off offset:256
	v_pk_fma_f32 v[48:49], v[48:49], v[78:79], v[74:75]
	global_load_dwordx4 v[54:57], v[54:55], off offset:256
	v_pk_fma_f32 v[74:75], v[44:45], v[80:81], v[76:77]
	global_load_dwordx4 v[58:61], v[58:59], off
	v_pk_fma_f32 v[44:45], v[42:43], v[84:85], v[88:89]
	global_load_dwordx4 v[62:65], v[62:63], off
	v_cvt_pk_bf16_f32 v42, v46, v47
	v_add_co_u32_e32 v46, vcc, s15, v158
	v_cvt_pk_bf16_f32 v43, v48, v49
	v_cvt_pk_bf16_f32 v44, v44, v45
	v_cvt_pk_bf16_f32 v45, v74, v75
	s_waitcnt vmcnt(6)
	v_lshlrev_b32_e32 v48, 16, v72
	v_addc_co_u32_e32 v47, vcc, 0, v159, vcc
	global_store_dwordx4 v[46:47], v[42:45], off
	v_and_b32_e32 v49, 0xffff0000, v72
	v_lshlrev_b32_e32 v72, 16, v66
	v_lshlrev_b32_e32 v42, 16, v70
	v_and_b32_e32 v43, 0xffff0000, v70
	v_lshlrev_b32_e32 v44, 16, v71
	v_and_b32_e32 v45, 0xffff0000, v71
	v_lshlrev_b32_e32 v70, 16, v73
	v_and_b32_e32 v71, 0xffff0000, v73
	v_and_b32_e32 v73, 0xffff0000, v66
	v_lshlrev_b32_e32 v74, 16, v68
	v_and_b32_e32 v75, 0xffff0000, v68
	v_lshlrev_b32_e32 v68, 16, v69
	v_and_b32_e32 v69, 0xffff0000, v69
	v_pk_fma_f32 v[38:39], v[38:39], v[42:43], v[72:73]
	s_mov_b32 s15, 0x58000
	v_lshlrev_b32_e32 v66, 16, v67
	v_and_b32_e32 v67, 0xffff0000, v67
	v_pk_fma_f32 v[42:43], v[36:37], v[70:71], v[68:69]
	v_pk_fma_f32 v[36:37], v[34:35], v[48:49], v[74:75]
	v_cvt_pk_bf16_f32 v34, v38, v39
	v_add_co_u32_e32 v38, vcc, s15, v162
	v_pk_fma_f32 v[40:41], v[40:41], v[44:45], v[66:67]
	s_mov_b64 s[12:13], 0x58000
	v_cvt_pk_bf16_f32 v35, v40, v41
	v_cvt_pk_bf16_f32 v36, v36, v37
	v_cvt_pk_bf16_f32 v37, v42, v43
	global_store_dwordx4 v[46:47], v[34:37], off offset:256
	v_addc_co_u32_e32 v39, vcc, 0, v163, vcc
	s_nop 0
	v_lshl_add_u64 v[34:35], v[162:163], 0, s[12:13]
	v_add_co_u32_e32 v46, vcc, s15, v160
	global_load_dwordx4 v[34:37], v[34:35], off offset:256
	s_nop 0
	v_addc_co_u32_e32 v47, vcc, 0, v161, vcc
	global_load_dwordx4 v[42:45], v[38:39], off
	v_lshl_add_u64 v[38:39], v[160:161], 0, s[12:13]
	global_load_dwordx4 v[38:41], v[38:39], off offset:256
	s_waitcnt vmcnt(6)
	v_lshlrev_b32_e32 v70, 16, v58
	global_load_dwordx4 v[46:49], v[46:47], off
	s_waitcnt vmcnt(6)
	v_lshlrev_b32_e32 v66, 16, v62
	v_and_b32_e32 v67, 0xffff0000, v62
	v_and_b32_e32 v71, 0xffff0000, v58
	v_lshlrev_b32_e32 v62, 16, v63
	v_and_b32_e32 v63, 0xffff0000, v63
	v_lshlrev_b32_e32 v68, 16, v64
	v_and_b32_e32 v69, 0xffff0000, v64
	v_lshlrev_b32_e32 v64, 16, v65
	v_and_b32_e32 v65, 0xffff0000, v65
	v_lshlrev_b32_e32 v58, 16, v59
	v_and_b32_e32 v59, 0xffff0000, v59
	v_lshlrev_b32_e32 v72, 16, v60
	v_and_b32_e32 v73, 0xffff0000, v60
	v_lshlrev_b32_e32 v60, 16, v61
	v_and_b32_e32 v61, 0xffff0000, v61
	v_pk_fma_f32 v[30:31], v[30:31], v[66:67], v[70:71]
	v_pk_fma_f32 v[32:33], v[32:33], v[62:63], v[58:59]
	v_pk_fma_f32 v[58:59], v[28:29], v[64:65], v[60:61]
	v_pk_fma_f32 v[28:29], v[26:27], v[68:69], v[72:73]
	v_cvt_pk_bf16_f32 v26, v30, v31
	v_add_co_u32_e32 v30, vcc, s11, v158
	v_cvt_pk_bf16_f32 v27, v32, v33
	v_cvt_pk_bf16_f32 v28, v28, v29
	v_cvt_pk_bf16_f32 v29, v58, v59
	v_lshlrev_b32_e32 v32, 16, v56
	s_nop 0
	v_addc_co_u32_e32 v31, vcc, 0, v159, vcc
	global_store_dwordx4 v[30:31], v[26:29], off
	v_and_b32_e32 v33, 0xffff0000, v56
	v_lshlrev_b32_e32 v56, 16, v50
	v_lshlrev_b32_e32 v26, 16, v54
	v_and_b32_e32 v27, 0xffff0000, v54
	v_lshlrev_b32_e32 v28, 16, v55
	v_and_b32_e32 v29, 0xffff0000, v55
	v_lshlrev_b32_e32 v54, 16, v57
	v_and_b32_e32 v55, 0xffff0000, v57
	v_and_b32_e32 v57, 0xffff0000, v50
	v_lshlrev_b32_e32 v50, 16, v51
	v_and_b32_e32 v51, 0xffff0000, v51
	v_lshlrev_b32_e32 v58, 16, v52
	v_and_b32_e32 v59, 0xffff0000, v52
	v_lshlrev_b32_e32 v52, 16, v53
	v_and_b32_e32 v53, 0xffff0000, v53
	v_pk_fma_f32 v[24:25], v[24:25], v[28:29], v[50:51]
	v_pk_fma_f32 v[22:23], v[22:23], v[26:27], v[56:57]
	v_pk_fma_f32 v[26:27], v[20:21], v[54:55], v[52:53]
	v_pk_fma_f32 v[20:21], v[18:19], v[32:33], v[58:59]
	v_cvt_pk_bf16_f32 v18, v22, v23
	v_cvt_pk_bf16_f32 v19, v24, v25
	s_waitcnt vmcnt(3)
	v_lshlrev_b32_e32 v32, 16, v45
	v_cvt_pk_bf16_f32 v20, v20, v21
	v_cvt_pk_bf16_f32 v21, v26, v27
	global_store_dwordx4 v[30:31], v[18:21], off offset:256
	v_lshlrev_b32_e32 v26, 16, v42
	v_and_b32_e32 v27, 0xffff0000, v42
	v_lshlrev_b32_e32 v30, 16, v44
	v_and_b32_e32 v31, 0xffff0000, v44
	v_and_b32_e32 v33, 0xffff0000, v45
	v_lshlrev_b32_e32 v28, 16, v43
	v_and_b32_e32 v29, 0xffff0000, v43
	s_waitcnt vmcnt(2)
	v_lshlrev_b32_e32 v18, 16, v46
	v_and_b32_e32 v19, 0xffff0000, v46
	v_lshlrev_b32_e32 v22, 16, v48
	v_and_b32_e32 v23, 0xffff0000, v48
	v_lshlrev_b32_e32 v24, 16, v49
	v_and_b32_e32 v25, 0xffff0000, v49
	v_pk_fma_f32 v[14:15], v[14:15], v[18:19], v[26:27]
	v_lshlrev_b32_e32 v20, 16, v47
	v_and_b32_e32 v21, 0xffff0000, v47
	v_pk_fma_f32 v[18:19], v[12:13], v[24:25], v[32:33]
	v_pk_fma_f32 v[12:13], v[10:11], v[22:23], v[30:31]
	v_cvt_pk_bf16_f32 v10, v14, v15
	v_add_co_u32_e32 v14, vcc, s15, v158
	v_pk_fma_f32 v[16:17], v[16:17], v[20:21], v[28:29]
	s_nop 0
	v_addc_co_u32_e32 v15, vcc, 0, v159, vcc
	v_cvt_pk_bf16_f32 v11, v16, v17
	v_cvt_pk_bf16_f32 v12, v12, v13
	v_cvt_pk_bf16_f32 v13, v18, v19
	global_store_dwordx4 v[14:15], v[10:13], off
	v_lshlrev_b32_e32 v16, 16, v40
	v_and_b32_e32 v17, 0xffff0000, v40
	v_lshlrev_b32_e32 v10, 16, v38
	v_and_b32_e32 v11, 0xffff0000, v38
	v_lshlrev_b32_e32 v18, 16, v41
	v_and_b32_e32 v19, 0xffff0000, v41
	v_lshlrev_b32_e32 v20, 16, v34
	v_and_b32_e32 v21, 0xffff0000, v34
	v_lshlrev_b32_e32 v24, 16, v36
	v_and_b32_e32 v25, 0xffff0000, v36
	v_lshlrev_b32_e32 v26, 16, v37
	v_and_b32_e32 v27, 0xffff0000, v37
	v_lshlrev_b32_e32 v12, 16, v39
	v_and_b32_e32 v13, 0xffff0000, v39
	v_lshlrev_b32_e32 v22, 16, v35
	v_and_b32_e32 v23, 0xffff0000, v35
	v_pk_fma_f32 v[6:7], v[6:7], v[10:11], v[20:21]
	v_pk_fma_f32 v[10:11], v[4:5], v[18:19], v[26:27]
	v_pk_fma_f32 v[4:5], v[2:3], v[16:17], v[24:25]
	v_pk_fma_f32 v[8:9], v[8:9], v[12:13], v[22:23]
	v_cvt_pk_bf16_f32 v2, v6, v7
	s_andn2_b64 vcc, exec, s[16:17]
	v_cvt_pk_bf16_f32 v3, v8, v9
	v_cvt_pk_bf16_f32 v4, v4, v5
	v_cvt_pk_bf16_f32 v5, v10, v11
	global_store_dwordx4 v[14:15], v[2:5], off offset:256
	s_cbranch_vccnz .LBB0_2269
	s_andn2_b64 vcc, exec, s[0:1]
	s_cbranch_vccnz .LBB0_2268
	s_barrier
	s_branch .LBB0_2268
